# v23 + final hand-off: sample out-projection WGs issue the combine-counter poll before the GEMM closing store drain, leaving only the acquire on the kernel tail
# speedup vs baseline: 1.0283x; 1.0283x over previous
; #define PG8_WAIT_V(n) asm volatile("s_waitcnt vmcnt(" #n ")" ::: "memory")
; #define PG8_BAR __builtin_amdgcn_s_barrier()
; template <class Epi>
; __device__ __forceinline__ void gemm_phase(LAS unsigned char* lds, const Gemm g, const Order& S, const Epi& E) {
;     ...
;     PG8_WAIT_V(0);
;     PG8_BAR;
; __global__ void __launch_bounds__(512, 2) hymba_fwd(Params p) {
;     ...
;         if (bx < 128) { sample_outproj(p, lds, bx); __syncthreads(); }
.LBB0_1218:
	s_cmpk_gt_i32 s95, 0x7f
	s_cbranch_scc1 .Lp5_nopre
	s_nop 2
	v_mov_b32_e32 v250, 0xc00
	s_nop 0
	global_load_dword v250, v250, s[90:91] sc1

; #define PSTAMP0(i) do { if (PROBE_SEG >= 40 && blockIdx.x == 0 && threadIdx.x == 0) ((volatile LAS unsigned long long*)(ctlw + 32))[20 + (i)] = __builtin_amdgcn_s_memrealtime(); } while (0)
; __global__ void __launch_bounds__(512, 2) hymba_fwd(Params p) {
;     ...
;         PSTAMP0(4);
;         if (bx < 128) { sample_outproj(p, lds, bx); __syncthreads(); }
;         PSTAMP0(5);
.LBB0_1219:
	s_cmp_eq_u32 s98, 4
	s_cbranch_scc0 .Lp5_exit
	v_readlane_b32 s0, v254, 4
	s_cmp_lt_i32 s0, 6
	s_cbranch_scc1 .Lp5_exit
	s_cmpk_gt_i32 s95, 0x7f
	s_cbranch_scc1 .Lp5_exit
	s_mov_b32 s98, 5
	v_mov_b32_e32 v0, v255
	s_waitcnt vmcnt(0) lgkmcnt(0)
	s_barrier
	v_cmp_eq_u32_e32 vcc, 0, v0
	s_and_saveexec_b64 s[0:1], vcc
	s_cbranch_execz .Lp5_pe
	s_mov_b32 s5, 0x8000
	v_mov_b32_e32 v2, 0xc00
	v_readfirstlane_b32 s4, v250
	s_cmpk_gt_u32 s4, 63
	s_cbranch_scc1 .Lp5_pd
